# retention chain loop: counted vmcnt waits corrected so the tiles requested at the start of a step are no longer forced to land within the same step (true 2-step prefetch distance)
# baseline (speedup 1.0000x reference)
; template <bool A_TR, bool B_TR>
; __device__ __forceinline__ void mm128(f32x4 (&acc)[8], ldsp TA, ldsp TB, int w, int lane) {
;     ...
; #pragma unroll
;     for (int ks = 0; ks < 4; ++ks) {
;         const bf16x8 a = A_TR ? frag_tr(ab, 0, ks) : frag_row(ab, 0, ks);
; #pragma unroll
;         for (int c = 0; c < 8; ++c) {
;             const bf16x8 b = B_TR ? frag_tr(bb, c, ks) : frag_row(bb, c, ks);
;             acc[c] = __builtin_amdgcn_mfma_f32_16x16x32_bf16(b, a, acc[c], 0, 0, 0);
;         }
;     }
.LBB0_307:
	s_ashr_i32 s11, s10, 31
	s_lshl_b64 s[18:19], s[10:11], 15
	v_lshl_add_u64 v[146:147], v[108:109], 0, s[18:19]
	v_cvt_pk_bf16_f32 v148, v66, v67
	v_cvt_pk_bf16_f32 v149, v68, v69
	global_store_dwordx2 v[146:147], v[148:149], off
	v_cvt_pk_bf16_f32 v148, v70, v71
	v_cvt_pk_bf16_f32 v149, v72, v73
	global_store_dwordx2 v[146:147], v[148:149], off offset:512
	v_cvt_pk_bf16_f32 v148, v74, v75
	v_cvt_pk_bf16_f32 v149, v76, v77
	global_store_dwordx2 v[146:147], v[148:149], off offset:1024
	v_cvt_pk_bf16_f32 v148, v78, v79
	v_cvt_pk_bf16_f32 v149, v80, v81
	global_store_dwordx2 v[146:147], v[148:149], off offset:1536
	v_cvt_pk_bf16_f32 v148, v82, v83
	v_cvt_pk_bf16_f32 v149, v84, v85
	global_store_dwordx2 v[146:147], v[148:149], off offset:2048
	v_cvt_pk_bf16_f32 v148, v86, v87
	v_cvt_pk_bf16_f32 v149, v88, v89
	global_store_dwordx2 v[146:147], v[148:149], off offset:2560
	v_cvt_pk_bf16_f32 v148, v90, v91
	v_cvt_pk_bf16_f32 v149, v92, v93
	global_store_dwordx2 v[146:147], v[148:149], off offset:3072
	v_cvt_pk_bf16_f32 v148, v94, v95
	v_cvt_pk_bf16_f32 v149, v96, v97
	v_pk_mul_f32 v[68:69], v[122:123], v[68:69]
	v_pk_mul_f32 v[66:67], v[112:113], v[66:67]
	v_pk_mul_f32 v[72:73], v[122:123], v[72:73]
	v_pk_mul_f32 v[70:71], v[112:113], v[70:71]
	v_pk_mul_f32 v[76:77], v[122:123], v[76:77]
	v_pk_mul_f32 v[74:75], v[112:113], v[74:75]
	v_pk_mul_f32 v[80:81], v[122:123], v[80:81]
	v_pk_mul_f32 v[78:79], v[112:113], v[78:79]
	v_pk_mul_f32 v[84:85], v[122:123], v[84:85]
	v_pk_mul_f32 v[82:83], v[112:113], v[82:83]
	v_pk_mul_f32 v[88:89], v[122:123], v[88:89]
	v_pk_mul_f32 v[86:87], v[112:113], v[86:87]
	v_pk_mul_f32 v[92:93], v[122:123], v[92:93]
	v_pk_mul_f32 v[90:91], v[112:113], v[90:91]
	v_pk_mul_f32 v[96:97], v[122:123], v[96:97]
	v_pk_mul_f32 v[94:95], v[112:113], v[94:95]
	global_store_dwordx2 v[146:147], v[148:149], off offset:3584
	s_setprio 1
	v_add_u32_e32 v158, s13, v136
	ds_read_b64_tr_b16 v[178:179], v158
	ds_read_b64_tr_b16 v[180:181], v158 offset:1088
	ds_read_b64_tr_b16 v[184:185], v136 offset:35904
	ds_read_b64_tr_b16 v[182:183], v136 offset:34816
	ds_read_b64_tr_b16 v[186:187], v136 offset:34880
	ds_read_b64_tr_b16 v[188:189], v136 offset:35968
	ds_read_b64_tr_b16 v[190:191], v136 offset:34912
	ds_read_b64_tr_b16 v[192:193], v136 offset:36000
	ds_read_b64_tr_b16 v[194:195], v136 offset:34944
	ds_read_b64_tr_b16 v[196:197], v136 offset:36032
	ds_read_b64_tr_b16 v[198:199], v136 offset:34976
	ds_read_b64_tr_b16 v[200:201], v136 offset:36064
	ds_read_b64_tr_b16 v[202:203], v136 offset:35008
	ds_read_b64_tr_b16 v[204:205], v136 offset:36096
	ds_read_b64_tr_b16 v[206:207], v136 offset:34848
	ds_read_b64_tr_b16 v[208:209], v136 offset:35936
	ds_read_b64_tr_b16 v[212:213], v136 offset:35040
	ds_read_b64_tr_b16 v[214:215], v136 offset:36128
	s_waitcnt lgkmcnt(14)
	v_mfma_f32_16x16x32_bf16 v[66:69], v[182:185], v[178:181], v[66:69]
	ds_read_b64_tr_b16 v[216:217], v158 offset:8704
	ds_read_b64_tr_b16 v[218:219], v158 offset:9792
	s_waitcnt lgkmcnt(14)
	v_mfma_f32_16x16x32_bf16 v[74:77], v[186:189], v[178:181], v[74:77]
	ds_read_b64_tr_b16 v[220:221], v136 offset:43520
	ds_read_b64_tr_b16 v[222:223], v136 offset:44608
	s_waitcnt lgkmcnt(14)
	v_mfma_f32_16x16x32_bf16 v[78:81], v[190:193], v[178:181], v[78:81]
	ds_read_b64_tr_b16 v[236:237], v136 offset:43552
	ds_read_b64_tr_b16 v[238:239], v136 offset:44640
	s_waitcnt lgkmcnt(14)
	v_mfma_f32_16x16x32_bf16 v[82:85], v[194:197], v[178:181], v[82:85]
	ds_read_b64_tr_b16 v[182:183], v136 offset:43584
	ds_read_b64_tr_b16 v[184:185], v136 offset:44672
	s_waitcnt lgkmcnt(14)
	v_mfma_f32_16x16x32_bf16 v[86:89], v[198:201], v[178:181], v[86:89]
	ds_read_b64_tr_b16 v[186:187], v136 offset:43616
	ds_read_b64_tr_b16 v[188:189], v136 offset:44704
	s_waitcnt lgkmcnt(14)
	v_mfma_f32_16x16x32_bf16 v[90:93], v[202:205], v[178:181], v[90:93]
	ds_read_b64_tr_b16 v[190:191], v136 offset:43648
	ds_read_b64_tr_b16 v[192:193], v136 offset:44736
	s_waitcnt lgkmcnt(14)
	v_mfma_f32_16x16x32_bf16 v[70:73], v[206:209], v[178:181], v[70:73]
	ds_read_b64_tr_b16 v[194:195], v136 offset:43680
	ds_read_b64_tr_b16 v[196:197], v136 offset:44768
	s_waitcnt lgkmcnt(14)
	v_mfma_f32_16x16x32_bf16 v[94:97], v[212:215], v[178:181], v[94:97]
	ds_read_b64_tr_b16 v[198:199], v136 offset:43712
	ds_read_b64_tr_b16 v[200:201], v136 offset:44800
	ds_read_b64_tr_b16 v[202:203], v136 offset:43744
	ds_read_b64_tr_b16 v[204:205], v136 offset:44832
	s_waitcnt lgkmcnt(14)
	v_mfma_f32_16x16x32_bf16 v[66:69], v[220:223], v[216:219], v[66:69]
	ds_read_b64_tr_b16 v[206:207], v158 offset:17408
	ds_read_b64_tr_b16 v[208:209], v158 offset:18496
	s_waitcnt lgkmcnt(14)
	v_mfma_f32_16x16x32_bf16 v[70:73], v[236:239], v[216:219], v[70:73]
	ds_read_b64_tr_b16 v[212:213], v136 offset:52224
	ds_read_b64_tr_b16 v[214:215], v136 offset:53312
	s_waitcnt lgkmcnt(14)
	v_mfma_f32_16x16x32_bf16 v[74:77], v[182:185], v[216:219], v[74:77]
	ds_read_b64_tr_b16 v[178:179], v136 offset:52256
	ds_read_b64_tr_b16 v[180:181], v136 offset:53344
	s_waitcnt lgkmcnt(14)
	v_mfma_f32_16x16x32_bf16 v[78:81], v[186:189], v[216:219], v[78:81]
	ds_read_b64_tr_b16 v[220:221], v136 offset:52288
	ds_read_b64_tr_b16 v[222:223], v136 offset:53376
	s_waitcnt lgkmcnt(14)
	v_mfma_f32_16x16x32_bf16 v[82:85], v[190:193], v[216:219], v[82:85]
	ds_read_b64_tr_b16 v[236:237], v136 offset:52320
	ds_read_b64_tr_b16 v[238:239], v136 offset:53408
	s_waitcnt lgkmcnt(14)
	v_mfma_f32_16x16x32_bf16 v[86:89], v[194:197], v[216:219], v[86:89]
	ds_read_b64_tr_b16 v[182:183], v136 offset:52352
	ds_read_b64_tr_b16 v[184:185], v136 offset:53440
	s_waitcnt lgkmcnt(14)
; __device__ __forceinline__ unsigned cvt_pk_bf16(float lo, float hi) { const f32x2c_t v = {lo, hi}; return __builtin_bit_cast(unsigned, __builtin_convertvector(v, bf16x2c_t)); }
; #define LAS __attribute__((address_space(3)))
; __device__ __forceinline__ float bf_lo(unsigned w) { return __uint_as_float(w << 16); }
; __device__ __forceinline__ float bf_hi(unsigned w) { return __uint_as_float(w & 0xffff0000u); }
; __device__ __forceinline__ void tile_put(ldsp T, const TileRegs& t, int tid) {
; #pragma unroll
;     for (int i = 0; i < 4; ++i) { const int ck = tid + 512 * i, r = ck >> 4, ch = ck & 15; *(LAS v4u*)(T + offb(r, ch)) = t.v[i]; }
; }
; __device__ __forceinline__ void tile_put_v(ldsp T, const TileRegs& t, int tid) {
; #pragma unroll
;     for (int i = 0; i < 4; ++i) { const int ck = tid + 512 * i, r = ck >> 4, ch = ck & 15; *(LAS v4u*)(T + offb_v(r, ch)) = t.v[i]; }
; }
; __device__ __forceinline__ void tile_put_scaled(ldsp T, const TileRegs& t, float l2, float a0, float a1, int tid) {
; #pragma unroll
;     for (int i = 0; i < 4; ++i) { const int ck = tid + 512 * i, r = ck >> 4, ch = ck & 15;
;         const float sc = __builtin_amdgcn_exp2f(l2 * (a0 + a1 * (float)r));
;         v4u o;
; #pragma unroll
;         for (int k = 0; k < 4; ++k) o[k] = cvt_pk_bf16(bf_lo(t.v[i][k]) * sc, bf_hi(t.v[i][k]) * sc);
;         *(LAS v4u*)(T + offb(r, ch)) = o; }
	v_mfma_f32_16x16x32_bf16 v[90:93], v[198:201], v[216:219], v[90:93]
	ds_read_b64_tr_b16 v[186:187], v136 offset:52384
	ds_read_b64_tr_b16 v[188:189], v136 offset:53472
	s_waitcnt lgkmcnt(14)
	v_mfma_f32_16x16x32_bf16 v[94:97], v[202:205], v[216:219], v[94:97]
	ds_read_b64_tr_b16 v[190:191], v136 offset:52416
	ds_read_b64_tr_b16 v[192:193], v136 offset:53504
	ds_read_b64_tr_b16 v[194:195], v136 offset:52448
	ds_read_b64_tr_b16 v[196:197], v136 offset:53536
	s_waitcnt lgkmcnt(14)
	v_mfma_f32_16x16x32_bf16 v[66:69], v[212:215], v[206:209], v[66:69]
	ds_read_b64_tr_b16 v[198:199], v158 offset:26112
	ds_read_b64_tr_b16 v[200:201], v158 offset:27200
	s_waitcnt lgkmcnt(14)
	v_mfma_f32_16x16x32_bf16 v[70:73], v[178:181], v[206:209], v[70:73]
	ds_read_b64_tr_b16 v[202:203], v136 offset:60928
	ds_read_b64_tr_b16 v[204:205], v136 offset:62016
	s_waitcnt lgkmcnt(14)
	v_mfma_f32_16x16x32_bf16 v[74:77], v[220:223], v[206:209], v[74:77]
	ds_read_b64_tr_b16 v[216:217], v136 offset:60960
	ds_read_b64_tr_b16 v[218:219], v136 offset:62048
	s_waitcnt lgkmcnt(14)
	v_mfma_f32_16x16x32_bf16 v[78:81], v[236:239], v[206:209], v[78:81]
	ds_read_b64_tr_b16 v[212:213], v136 offset:60992
	ds_read_b64_tr_b16 v[214:215], v136 offset:62080
	s_waitcnt lgkmcnt(14)
	v_mfma_f32_16x16x32_bf16 v[82:85], v[182:185], v[206:209], v[82:85]
	ds_read_b64_tr_b16 v[178:179], v136 offset:61024
	ds_read_b64_tr_b16 v[180:181], v136 offset:62112
	s_waitcnt lgkmcnt(14)
	v_mfma_f32_16x16x32_bf16 v[86:89], v[186:189], v[206:209], v[86:89]
	ds_read_b64_tr_b16 v[220:221], v136 offset:61056
	ds_read_b64_tr_b16 v[222:223], v136 offset:62144
	s_waitcnt lgkmcnt(14)
	v_mfma_f32_16x16x32_bf16 v[90:93], v[190:193], v[206:209], v[90:93]
	ds_read_b64_tr_b16 v[236:237], v136 offset:61088
	ds_read_b64_tr_b16 v[238:239], v136 offset:62176
	s_waitcnt lgkmcnt(14)
	v_mfma_f32_16x16x32_bf16 v[94:97], v[194:197], v[206:209], v[94:97]
	ds_read_b64_tr_b16 v[182:183], v136 offset:61120
	ds_read_b64_tr_b16 v[184:185], v136 offset:62208
	ds_read_b64_tr_b16 v[186:187], v136 offset:61152
	ds_read_b64_tr_b16 v[188:189], v136 offset:62240
	s_waitcnt lgkmcnt(14)
	v_mfma_f32_16x16x32_bf16 v[66:69], v[202:205], v[198:201], v[66:69]
	s_waitcnt lgkmcnt(12)
	v_mfma_f32_16x16x32_bf16 v[70:73], v[216:219], v[198:201], v[70:73]
	s_waitcnt lgkmcnt(10)
	v_mfma_f32_16x16x32_bf16 v[74:77], v[212:215], v[198:201], v[74:77]
	s_waitcnt lgkmcnt(8)
	v_mfma_f32_16x16x32_bf16 v[78:81], v[178:181], v[198:201], v[78:81]
	s_waitcnt lgkmcnt(6)
	v_mfma_f32_16x16x32_bf16 v[82:85], v[220:223], v[198:201], v[82:85]
	s_waitcnt lgkmcnt(4)
	v_mfma_f32_16x16x32_bf16 v[86:89], v[236:239], v[198:201], v[86:89]
	s_waitcnt lgkmcnt(2)
	v_mfma_f32_16x16x32_bf16 v[90:93], v[182:185], v[198:201], v[90:93]
	s_waitcnt lgkmcnt(0)
	v_mfma_f32_16x16x32_bf16 v[94:97], v[186:189], v[198:201], v[94:97]
	s_nop 7
	s_setprio 0
	v_add_u32_e32 v146, v137, v129
	s_waitcnt vmcnt(20)
	ds_write_b128 v146, v[22:25]
	v_add_u32_e32 v146, v137, v130
	ds_write_b128 v146, v[30:33]
	v_add_u32_e32 v146, v137, v131
	ds_write_b128 v146, v[38:41]
	v_add_u32_e32 v146, v137, v132
	ds_write_b128 v146, v[46:49]
	s_waitcnt vmcnt(19)
	v_lshlrev_b32_e32 v146, 16, v50
	v_and_b32_e32 v147, 0xffff0000, v50
	v_lshlrev_b32_e32 v148, 16, v51
	v_and_b32_e32 v149, 0xffff0000, v51
	v_pk_mul_f32 v[146:147], v[114:115], v[146:147]
	v_pk_mul_f32 v[148:149], v[114:115], v[148:149]
	v_cvt_pk_bf16_f32 v146, v146, v147
	v_cvt_pk_bf16_f32 v147, v148, v149
	v_lshlrev_b32_e32 v148, 16, v52
	v_and_b32_e32 v149, 0xffff0000, v52
	v_lshlrev_b32_e32 v150, 16, v53
	v_and_b32_e32 v151, 0xffff0000, v53
	v_pk_mul_f32 v[148:149], v[114:115], v[148:149]
	v_pk_mul_f32 v[150:151], v[114:115], v[150:151]
	v_cvt_pk_bf16_f32 v148, v148, v149
	v_cvt_pk_bf16_f32 v149, v150, v151
	v_add_u32_e32 v150, v138, v129
	ds_write_b128 v150, v[146:149]
	s_waitcnt vmcnt(18)
	v_lshlrev_b32_e32 v146, 16, v54
	v_and_b32_e32 v147, 0xffff0000, v54
	v_lshlrev_b32_e32 v148, 16, v55
	v_and_b32_e32 v149, 0xffff0000, v55
	v_pk_mul_f32 v[146:147], v[116:117], v[146:147]
	v_pk_mul_f32 v[148:149], v[116:117], v[148:149]
	v_cvt_pk_bf16_f32 v146, v146, v147
	v_cvt_pk_bf16_f32 v147, v148, v149
	v_lshlrev_b32_e32 v148, 16, v56
	v_and_b32_e32 v149, 0xffff0000, v56
	v_lshlrev_b32_e32 v150, 16, v57
	v_and_b32_e32 v151, 0xffff0000, v57
	v_pk_mul_f32 v[148:149], v[116:117], v[148:149]
	v_pk_mul_f32 v[150:151], v[116:117], v[150:151]
	v_cvt_pk_bf16_f32 v148, v148, v149
	v_cvt_pk_bf16_f32 v149, v150, v151
	v_add_u32_e32 v150, v138, v130
	ds_write_b128 v150, v[146:149]
	s_waitcnt vmcnt(17)
	v_lshlrev_b32_e32 v146, 16, v58
	v_and_b32_e32 v147, 0xffff0000, v58
	v_lshlrev_b32_e32 v148, 16, v59
	v_and_b32_e32 v149, 0xffff0000, v59
	v_pk_mul_f32 v[146:147], v[118:119], v[146:147]
	v_pk_mul_f32 v[148:149], v[118:119], v[148:149]
	v_cvt_pk_bf16_f32 v146, v146, v147
	v_cvt_pk_bf16_f32 v147, v148, v149
	v_lshlrev_b32_e32 v148, 16, v60
	v_and_b32_e32 v149, 0xffff0000, v60
	v_lshlrev_b32_e32 v150, 16, v61
	v_and_b32_e32 v151, 0xffff0000, v61
	v_pk_mul_f32 v[148:149], v[118:119], v[148:149]
	v_pk_mul_f32 v[150:151], v[118:119], v[150:151]
	v_cvt_pk_bf16_f32 v148, v148, v149
	v_cvt_pk_bf16_f32 v149, v150, v151
	v_add_u32_e32 v150, v138, v131
	ds_write_b128 v150, v[146:149]
	s_waitcnt vmcnt(16)
	v_lshlrev_b32_e32 v146, 16, v62
	v_and_b32_e32 v147, 0xffff0000, v62
	v_lshlrev_b32_e32 v148, 16, v63
	v_and_b32_e32 v149, 0xffff0000, v63
	v_pk_mul_f32 v[146:147], v[120:121], v[146:147]
	v_pk_mul_f32 v[148:149], v[120:121], v[148:149]
	v_cvt_pk_bf16_f32 v146, v146, v147
	v_cvt_pk_bf16_f32 v147, v148, v149
	v_lshlrev_b32_e32 v148, 16, v64
	v_and_b32_e32 v149, 0xffff0000, v64
	v_lshlrev_b32_e32 v150, 16, v65
	v_and_b32_e32 v151, 0xffff0000, v65
	v_pk_mul_f32 v[148:149], v[120:121], v[148:149]
	v_pk_mul_f32 v[150:151], v[120:121], v[150:151]
	v_cvt_pk_bf16_f32 v148, v148, v149
	v_cvt_pk_bf16_f32 v149, v150, v151
	v_add_u32_e32 v150, v138, v132
	s_cmp_gt_u32 s4, 28
	ds_write_b128 v150, v[146:149]
	s_waitcnt lgkmcnt(0)
	s_barrier
; __device__ __forceinline__ void tile_fetch(TileRegs& t, const bf16* src, size_t ld, int tid) {
; #pragma unroll
;     for (int i = 0; i < 4; ++i) { const int ck = tid + 512 * i, r = ck >> 4, ch = ck & 15; t.v[i] = *(const v4u*)(src + (size_t)r * ld + 8 * ch); }
; }
	s_cbranch_scc1 .LBB0_309
	s_mul_i32 s11, s5, 0x360000
	s_add_i32 s18, s11, s12
	s_ashr_i32 s19, s18, 31
	s_lshl_b64 s[18:19], s[18:19], 1
	s_add_u32 s18, s0, s18
	s_addc_u32 s19, s1, s19
	v_lshl_add_u64 v[50:51], s[18:19], 0, v[16:17]
	v_lshl_add_u64 v[38:39], v[50:51], 0, s[30:31]
	v_lshl_add_u64 v[58:59], v[50:51], 0, s[48:49]
	v_lshl_add_u64 v[22:23], v[38:39], 0, v[100:101]
	v_lshl_add_u64 v[30:31], v[38:39], 0, v[102:103]
	v_lshl_add_u64 v[40:41], v[38:39], 0, v[104:105]
	v_lshl_add_u64 v[46:47], v[38:39], 0, v[106:107]
	v_lshl_add_u64 v[50:51], v[58:59], 0, v[100:101]
	v_lshl_add_u64 v[54:55], v[58:59], 0, v[102:103]
	v_lshl_add_u64 v[60:61], v[58:59], 0, v[104:105]
	v_lshl_add_u64 v[62:63], v[58:59], 0, v[106:107]
	global_load_dwordx4 v[22:25], v[22:23], off
	s_nop 0
	global_load_dwordx4 v[30:33], v[30:31], off
	s_nop 0
	global_load_dwordx4 v[38:41], v[40:41], off
	s_nop 0
	global_load_dwordx4 v[46:49], v[46:47], off
	s_nop 0
	global_load_dwordx4 v[50:53], v[50:51], off
	s_nop 0
	global_load_dwordx4 v[54:57], v[54:55], off
	s_nop 0
	global_load_dwordx4 v[58:61], v[60:61], off
	s_nop 0
	global_load_dwordx4 v[62:65], v[62:63], off
.LBB0_309:
	s_add_i32 s18, s5, s10
	s_ashr_i32 s19, s18, 31
	s_lshl_b64 s[18:19], s[18:19], 15
	v_lshl_add_u64 v[146:147], v[108:109], 0, s[18:19]
	v_cvt_pk_bf16_f32 v148, v66, v67
	v_cvt_pk_bf16_f32 v149, v68, v69
	global_store_dwordx2 v[146:147], v[148:149], off
	v_cvt_pk_bf16_f32 v148, v70, v71
	v_cvt_pk_bf16_f32 v149, v72, v73
	global_store_dwordx2 v[146:147], v[148:149], off offset:512
	v_cvt_pk_bf16_f32 v148, v74, v75
	v_cvt_pk_bf16_f32 v149, v76, v77
	global_store_dwordx2 v[146:147], v[148:149], off offset:1024
	v_cvt_pk_bf16_f32 v148, v78, v79
	v_cvt_pk_bf16_f32 v149, v80, v81
	global_store_dwordx2 v[146:147], v[148:149], off offset:1536
	v_cvt_pk_bf16_f32 v148, v82, v83
	v_cvt_pk_bf16_f32 v149, v84, v85
	global_store_dwordx2 v[146:147], v[148:149], off offset:2048
	v_cvt_pk_bf16_f32 v148, v86, v87
	v_cvt_pk_bf16_f32 v149, v88, v89
	global_store_dwordx2 v[146:147], v[148:149], off offset:2560
	v_cvt_pk_bf16_f32 v148, v90, v91
	v_cvt_pk_bf16_f32 v149, v92, v93
	global_store_dwordx2 v[146:147], v[148:149], off offset:3072
	v_cvt_pk_bf16_f32 v148, v94, v95
	v_cvt_pk_bf16_f32 v149, v96, v97
	s_andn2_b64 vcc, exec, s[24:25]
	global_store_dwordx2 v[146:147], v[148:149], off offset:3584
	s_cbranch_vccnz .LBB0_304
	v_pk_mul_f32 v[68:69], v[122:123], v[68:69]
	v_pk_mul_f32 v[66:67], v[112:113], v[66:67]
	v_pk_mul_f32 v[72:73], v[122:123], v[72:73]
	v_pk_mul_f32 v[70:71], v[112:113], v[70:71]
	v_pk_mul_f32 v[76:77], v[122:123], v[76:77]
	v_pk_mul_f32 v[74:75], v[112:113], v[74:75]
	v_pk_mul_f32 v[80:81], v[122:123], v[80:81]
	v_pk_mul_f32 v[78:79], v[112:113], v[78:79]
	v_pk_mul_f32 v[84:85], v[122:123], v[84:85]
	v_pk_mul_f32 v[82:83], v[112:113], v[82:83]
	v_pk_mul_f32 v[88:89], v[122:123], v[88:89]
	v_pk_mul_f32 v[86:87], v[112:113], v[86:87]
	v_pk_mul_f32 v[92:93], v[122:123], v[92:93]
	v_pk_mul_f32 v[90:91], v[112:113], v[90:91]
	v_pk_mul_f32 v[96:97], v[122:123], v[96:97]
	v_pk_mul_f32 v[94:95], v[112:113], v[94:95]
	s_setprio 1
	ds_read_b64_tr_b16 v[178:179], v145
	ds_read_b64_tr_b16 v[180:181], v145 offset:1088
	ds_read_b64_tr_b16 v[184:185], v140 offset:1088
	ds_read_b64_tr_b16 v[182:183], v140
	ds_read_b64_tr_b16 v[186:187], v140 offset:64
	ds_read_b64_tr_b16 v[188:189], v140 offset:1152
	ds_read_b64_tr_b16 v[190:191], v140 offset:96
	ds_read_b64_tr_b16 v[192:193], v140 offset:1184
	ds_read_b64_tr_b16 v[194:195], v140 offset:128
	ds_read_b64_tr_b16 v[196:197], v140 offset:1216
	ds_read_b64_tr_b16 v[198:199], v140 offset:160
	ds_read_b64_tr_b16 v[200:201], v140 offset:1248
	ds_read_b64_tr_b16 v[202:203], v140 offset:192
	ds_read_b64_tr_b16 v[204:205], v140 offset:1280
	ds_read_b64_tr_b16 v[206:207], v140 offset:32
	ds_read_b64_tr_b16 v[208:209], v140 offset:1120
	ds_read_b64_tr_b16 v[212:213], v140 offset:224
	ds_read_b64_tr_b16 v[214:215], v140 offset:1312
	s_waitcnt lgkmcnt(14)
	v_mfma_f32_16x16x32_bf16 v[66:69], v[182:185], v[178:181], v[66:69]
	ds_read_b64_tr_b16 v[216:217], v145 offset:8704
	ds_read_b64_tr_b16 v[218:219], v145 offset:9792
	s_waitcnt lgkmcnt(14)
	v_mfma_f32_16x16x32_bf16 v[74:77], v[186:189], v[178:181], v[74:77]
	ds_read_b64_tr_b16 v[220:221], v140 offset:8704
	ds_read_b64_tr_b16 v[222:223], v140 offset:9792
	s_waitcnt lgkmcnt(14)
	v_mfma_f32_16x16x32_bf16 v[78:81], v[190:193], v[178:181], v[78:81]
	ds_read_b64_tr_b16 v[236:237], v140 offset:8736
	ds_read_b64_tr_b16 v[238:239], v140 offset:9824
	s_waitcnt lgkmcnt(14)
	v_mfma_f32_16x16x32_bf16 v[82:85], v[194:197], v[178:181], v[82:85]
	ds_read_b64_tr_b16 v[182:183], v140 offset:8768
	ds_read_b64_tr_b16 v[184:185], v140 offset:9856
	s_waitcnt lgkmcnt(14)
	v_mfma_f32_16x16x32_bf16 v[86:89], v[198:201], v[178:181], v[86:89]
	ds_read_b64_tr_b16 v[186:187], v140 offset:8800
	ds_read_b64_tr_b16 v[188:189], v140 offset:9888
	s_waitcnt lgkmcnt(14)
	v_mfma_f32_16x16x32_bf16 v[90:93], v[202:205], v[178:181], v[90:93]
	ds_read_b64_tr_b16 v[190:191], v140 offset:8832
	ds_read_b64_tr_b16 v[192:193], v140 offset:9920
	s_waitcnt lgkmcnt(14)
	v_mfma_f32_16x16x32_bf16 v[70:73], v[206:209], v[178:181], v[70:73]
	ds_read_b64_tr_b16 v[194:195], v140 offset:8864
	ds_read_b64_tr_b16 v[196:197], v140 offset:9952
	s_waitcnt lgkmcnt(14)
	v_mfma_f32_16x16x32_bf16 v[94:97], v[212:215], v[178:181], v[94:97]
	ds_read_b64_tr_b16 v[198:199], v140 offset:8896
	ds_read_b64_tr_b16 v[200:201], v140 offset:9984
	ds_read_b64_tr_b16 v[202:203], v140 offset:8928
	ds_read_b64_tr_b16 v[204:205], v140 offset:10016
	s_waitcnt lgkmcnt(14)
; __device__ __forceinline__ unsigned cvt_pk_bf16(float lo, float hi) { const f32x2c_t v = {lo, hi}; return __builtin_bit_cast(unsigned, __builtin_convertvector(v, bf16x2c_t)); }
; #define LAS __attribute__((address_space(3)))
; __device__ __forceinline__ float bf_lo(unsigned w) { return __uint_as_float(w << 16); }
; __device__ __forceinline__ float bf_hi(unsigned w) { return __uint_as_float(w & 0xffff0000u); }
; __device__ __forceinline__ void tile_put(ldsp T, const TileRegs& t, int tid) {
; #pragma unroll
;     for (int i = 0; i < 4; ++i) { const int ck = tid + 512 * i, r = ck >> 4, ch = ck & 15; *(LAS v4u*)(T + offb(r, ch)) = t.v[i]; }
; }
; __device__ __forceinline__ void tile_put_v(ldsp T, const TileRegs& t, int tid) {
; #pragma unroll
;     for (int i = 0; i < 4; ++i) { const int ck = tid + 512 * i, r = ck >> 4, ch = ck & 15; *(LAS v4u*)(T + offb_v(r, ch)) = t.v[i]; }
; }
; __device__ __forceinline__ void tile_put_scaled(ldsp T, const TileRegs& t, float l2, float a0, float a1, int tid) {
; #pragma unroll
;     for (int i = 0; i < 4; ++i) { const int ck = tid + 512 * i, r = ck >> 4, ch = ck & 15;
;         const float sc = __builtin_amdgcn_exp2f(l2 * (a0 + a1 * (float)r));
;         v4u o;
; #pragma unroll
;         for (int k = 0; k < 4; ++k) o[k] = cvt_pk_bf16(bf_lo(t.v[i][k]) * sc, bf_hi(t.v[i][k]) * sc);
;         *(LAS v4u*)(T + offb(r, ch)) = o; }
	v_mfma_f32_16x16x32_bf16 v[66:69], v[220:223], v[216:219], v[66:69]
	ds_read_b64_tr_b16 v[206:207], v145 offset:17408
	ds_read_b64_tr_b16 v[208:209], v145 offset:18496
	s_waitcnt lgkmcnt(14)
	v_mfma_f32_16x16x32_bf16 v[70:73], v[236:239], v[216:219], v[70:73]
	ds_read_b64_tr_b16 v[212:213], v140 offset:17408
	ds_read_b64_tr_b16 v[214:215], v140 offset:18496
	s_waitcnt lgkmcnt(14)
	v_mfma_f32_16x16x32_bf16 v[74:77], v[182:185], v[216:219], v[74:77]
	ds_read_b64_tr_b16 v[178:179], v140 offset:17440
	ds_read_b64_tr_b16 v[180:181], v140 offset:18528
	s_waitcnt lgkmcnt(14)
	v_mfma_f32_16x16x32_bf16 v[78:81], v[186:189], v[216:219], v[78:81]
	ds_read_b64_tr_b16 v[220:221], v140 offset:17472
	ds_read_b64_tr_b16 v[222:223], v140 offset:18560
	s_waitcnt lgkmcnt(14)
	v_mfma_f32_16x16x32_bf16 v[82:85], v[190:193], v[216:219], v[82:85]
	ds_read_b64_tr_b16 v[236:237], v140 offset:17504
	ds_read_b64_tr_b16 v[238:239], v140 offset:18592
	s_waitcnt lgkmcnt(14)
	v_mfma_f32_16x16x32_bf16 v[86:89], v[194:197], v[216:219], v[86:89]
	ds_read_b64_tr_b16 v[182:183], v140 offset:17536
	ds_read_b64_tr_b16 v[184:185], v140 offset:18624
	s_waitcnt lgkmcnt(14)
	v_mfma_f32_16x16x32_bf16 v[90:93], v[198:201], v[216:219], v[90:93]
	ds_read_b64_tr_b16 v[186:187], v140 offset:17568
	ds_read_b64_tr_b16 v[188:189], v140 offset:18656
	s_waitcnt lgkmcnt(14)
	v_mfma_f32_16x16x32_bf16 v[94:97], v[202:205], v[216:219], v[94:97]
	ds_read_b64_tr_b16 v[190:191], v140 offset:17600
	ds_read_b64_tr_b16 v[192:193], v140 offset:18688
	ds_read_b64_tr_b16 v[194:195], v140 offset:17632
	ds_read_b64_tr_b16 v[196:197], v140 offset:18720
	s_waitcnt lgkmcnt(14)
	v_mfma_f32_16x16x32_bf16 v[66:69], v[212:215], v[206:209], v[66:69]
	ds_read_b64_tr_b16 v[198:199], v145 offset:26112
	ds_read_b64_tr_b16 v[200:201], v145 offset:27200
	s_waitcnt lgkmcnt(14)
	v_mfma_f32_16x16x32_bf16 v[70:73], v[178:181], v[206:209], v[70:73]
	ds_read_b64_tr_b16 v[202:203], v140 offset:26112
	ds_read_b64_tr_b16 v[204:205], v140 offset:27200
	s_waitcnt lgkmcnt(14)
	v_mfma_f32_16x16x32_bf16 v[74:77], v[220:223], v[206:209], v[74:77]
	ds_read_b64_tr_b16 v[216:217], v140 offset:26144
	ds_read_b64_tr_b16 v[218:219], v140 offset:27232
	s_waitcnt lgkmcnt(14)
	v_mfma_f32_16x16x32_bf16 v[78:81], v[236:239], v[206:209], v[78:81]
	ds_read_b64_tr_b16 v[212:213], v140 offset:26176
	ds_read_b64_tr_b16 v[214:215], v140 offset:27264
	s_waitcnt lgkmcnt(14)
	v_mfma_f32_16x16x32_bf16 v[82:85], v[182:185], v[206:209], v[82:85]
	ds_read_b64_tr_b16 v[178:179], v140 offset:26208
	ds_read_b64_tr_b16 v[180:181], v140 offset:27296
	s_waitcnt lgkmcnt(14)
	v_mfma_f32_16x16x32_bf16 v[86:89], v[186:189], v[206:209], v[86:89]
	ds_read_b64_tr_b16 v[220:221], v140 offset:26240
	ds_read_b64_tr_b16 v[222:223], v140 offset:27328
	s_waitcnt lgkmcnt(14)
	v_mfma_f32_16x16x32_bf16 v[90:93], v[190:193], v[206:209], v[90:93]
	ds_read_b64_tr_b16 v[236:237], v140 offset:26272
	ds_read_b64_tr_b16 v[238:239], v140 offset:27360
	s_waitcnt lgkmcnt(14)
	v_mfma_f32_16x16x32_bf16 v[94:97], v[194:197], v[206:209], v[94:97]
	ds_read_b64_tr_b16 v[182:183], v140 offset:26304
	ds_read_b64_tr_b16 v[184:185], v140 offset:27392
	ds_read_b64_tr_b16 v[186:187], v140 offset:26336
	ds_read_b64_tr_b16 v[188:189], v140 offset:27424
	s_waitcnt lgkmcnt(14)
	v_mfma_f32_16x16x32_bf16 v[66:69], v[202:205], v[198:201], v[66:69]
	s_waitcnt lgkmcnt(12)
	v_mfma_f32_16x16x32_bf16 v[70:73], v[216:219], v[198:201], v[70:73]
	s_waitcnt lgkmcnt(10)
	v_mfma_f32_16x16x32_bf16 v[74:77], v[212:215], v[198:201], v[74:77]
	s_waitcnt lgkmcnt(8)
	v_mfma_f32_16x16x32_bf16 v[78:81], v[178:181], v[198:201], v[78:81]
	s_waitcnt lgkmcnt(6)
	v_mfma_f32_16x16x32_bf16 v[82:85], v[220:223], v[198:201], v[82:85]
	s_waitcnt lgkmcnt(4)
	v_mfma_f32_16x16x32_bf16 v[86:89], v[236:239], v[198:201], v[86:89]
	s_waitcnt lgkmcnt(2)
	v_mfma_f32_16x16x32_bf16 v[90:93], v[182:185], v[198:201], v[90:93]
	s_waitcnt lgkmcnt(0)
	v_mfma_f32_16x16x32_bf16 v[94:97], v[186:189], v[198:201], v[94:97]
	s_nop 7
	s_setprio 0
	s_waitcnt vmcnt(27)
	v_lshlrev_b32_e32 v146, 16, v18
	v_and_b32_e32 v147, 0xffff0000, v18
	v_lshlrev_b32_e32 v148, 16, v19
	v_and_b32_e32 v149, 0xffff0000, v19
	v_pk_mul_f32 v[146:147], v[114:115], v[146:147]
	v_pk_mul_f32 v[148:149], v[114:115], v[148:149]
	v_cvt_pk_bf16_f32 v146, v146, v147
	v_cvt_pk_bf16_f32 v147, v148, v149
	v_lshlrev_b32_e32 v148, 16, v20
	v_and_b32_e32 v149, 0xffff0000, v20
	v_lshlrev_b32_e32 v150, 16, v21
	v_and_b32_e32 v151, 0xffff0000, v21
	v_pk_mul_f32 v[148:149], v[114:115], v[148:149]
	v_pk_mul_f32 v[150:151], v[114:115], v[150:151]
	v_cvt_pk_bf16_f32 v148, v148, v149
	v_cvt_pk_bf16_f32 v149, v150, v151
	ds_write_b128 v99, v[0:3]
	ds_write_b128 v142, v[4:7]
	ds_write_b128 v143, v[8:11]
	ds_write_b128 v144, v[12:15]
	ds_write_b128 v99, v[146:149] offset:34816
	s_waitcnt vmcnt(26)
	v_lshlrev_b32_e32 v146, 16, v26
	v_and_b32_e32 v147, 0xffff0000, v26
	v_lshlrev_b32_e32 v148, 16, v27
	v_and_b32_e32 v149, 0xffff0000, v27
	v_pk_mul_f32 v[146:147], v[116:117], v[146:147]
	v_pk_mul_f32 v[148:149], v[116:117], v[148:149]
	v_cvt_pk_bf16_f32 v146, v146, v147
	v_cvt_pk_bf16_f32 v147, v148, v149
	v_lshlrev_b32_e32 v148, 16, v28
	v_and_b32_e32 v149, 0xffff0000, v28
	v_lshlrev_b32_e32 v150, 16, v29
	v_and_b32_e32 v151, 0xffff0000, v29
	v_pk_mul_f32 v[148:149], v[116:117], v[148:149]
	v_pk_mul_f32 v[150:151], v[116:117], v[150:151]
	v_cvt_pk_bf16_f32 v148, v148, v149
	v_cvt_pk_bf16_f32 v149, v150, v151
	ds_write_b128 v142, v[146:149] offset:34816
	s_waitcnt vmcnt(25)
	v_lshlrev_b32_e32 v146, 16, v34
	v_and_b32_e32 v147, 0xffff0000, v34
	v_lshlrev_b32_e32 v148, 16, v35
	v_and_b32_e32 v149, 0xffff0000, v35
	v_pk_mul_f32 v[146:147], v[118:119], v[146:147]
	v_pk_mul_f32 v[148:149], v[118:119], v[148:149]
	v_cvt_pk_bf16_f32 v146, v146, v147
	v_cvt_pk_bf16_f32 v147, v148, v149
	v_lshlrev_b32_e32 v148, 16, v36
	v_and_b32_e32 v149, 0xffff0000, v36
	v_lshlrev_b32_e32 v150, 16, v37
	v_and_b32_e32 v151, 0xffff0000, v37
	v_pk_mul_f32 v[148:149], v[118:119], v[148:149]
	v_pk_mul_f32 v[150:151], v[118:119], v[150:151]
	v_cvt_pk_bf16_f32 v148, v148, v149
	v_cvt_pk_bf16_f32 v149, v150, v151
	ds_write_b128 v143, v[146:149] offset:34816
	s_waitcnt vmcnt(24)
	v_lshlrev_b32_e32 v146, 16, v42
	v_and_b32_e32 v147, 0xffff0000, v42
	v_lshlrev_b32_e32 v148, 16, v43
	v_and_b32_e32 v149, 0xffff0000, v43
	v_pk_mul_f32 v[146:147], v[120:121], v[146:147]
	v_pk_mul_f32 v[148:149], v[120:121], v[148:149]
	v_cvt_pk_bf16_f32 v146, v146, v147
	v_cvt_pk_bf16_f32 v147, v148, v149
	v_lshlrev_b32_e32 v148, 16, v44
	v_and_b32_e32 v149, 0xffff0000, v44
	v_lshlrev_b32_e32 v150, 16, v45
	v_and_b32_e32 v151, 0xffff0000, v45
	v_pk_mul_f32 v[148:149], v[120:121], v[148:149]
	v_pk_mul_f32 v[150:151], v[120:121], v[150:151]
	v_cvt_pk_bf16_f32 v148, v148, v149
	v_cvt_pk_bf16_f32 v149, v150, v151
	ds_write_b128 v144, v[146:149] offset:34816
	s_branch .LBB0_304
